# P11 epilogue: GELU argument evaluated with packed f32 ops on element pairs ((A x^2+B) x, constants folded) and dead DPP-destination inits removed
# speedup vs baseline: 1.0036x; 1.0036x over previous
;     DI void operator()(const f32x4 (&acc)[2][2][4][2], const pg8::Unit& u, int wr, int wc, int fr, int fq) const {
;     ...
;         float4 w0v[2], w1v[2], w2v[2], bbv[2];
; #pragma unroll
;         for (int bj = 0; bj < 2; ++bj) {
;             const int hc = (u.pn * 256 + bj * 128 + wc * 32 + 8 * fq) >> 1;
;             w0v[bj] = *(const float4*)(cw + hc); w1v[bj] = *(const float4*)(cw + FH + hc); w2v[bj] = *(const float4*)(cw + 2 * FH + hc); bbv[bj] = *(const float4*)(cb + hc);
;         }
; #pragma unroll
;         for (int bj = 0; bj < 2; ++bj) {
;             const int hc = (u.pn * 256 + bj * 128 + wc * 32 + 8 * fq) >> 1;
;             const float4 w0 = w0v[bj], w1 = w1v[bj], w2 = w2v[bj], bb = bbv[bj];
; #pragma unroll
;             for (int ai = 0; ai < 2; ++ai) {
;                 f32x4 gprev = (f32x4){0.f, 0.f, 0.f, 0.f};
; #pragma unroll
;                 for (int m = 0; m < 4; ++m) {
;                     const f32x4 v = acc[ai][bj][m][0], g = acc[ai][bj][m][1];
;                     f32x4 p1, p2;
; #pragma unroll
;                     for (int r = 0; r < 4; ++r) {
;                         p1[r] = __builtin_bit_cast(float, __builtin_amdgcn_update_dpp(0, __builtin_bit_cast(int, (fr == 15) ? gprev[r] : g[r]), 0x121, 0xF, 0xF, false));
;                         p2[r] = __builtin_bit_cast(float, __builtin_amdgcn_update_dpp(0, __builtin_bit_cast(int, (fr >= 14) ? gprev[r] : g[r]), 0x122, 0xF, 0xF, false));
;                     }
;                     const int row = u.pm * 256 + ai * 128 + wr * 64 + m * 16 + fr;
;                     const int wb = row >> 6;
;                     if (m == 0 && fr < 2) {
;                         *(f32x4*)(gfirst + ((size_t)wb * 2 + fr) * FH + hc) = g;
;                         *(f32x4*)(vfirst + ((size_t)wb * 2 + fr) * FH + hc) = v;
;                     } else {
;                         f32x4 o;
;                         o[0] = gelu_t(bb.x + w0.x * p2[0] + w1.x * p1[0] + w2.x * g[0]) * v[0];
;                         o[1] = gelu_t(bb.y + w0.y * p2[1] + w1.y * p1[1] + w2.y * g[1]) * v[1];
;                         o[2] = gelu_t(bb.z + w0.z * p2[2] + w1.z * p1[2] + w2.z * g[2]) * v[2];
;                         o[3] = gelu_t(bb.w + w0.w * p2[3] + w1.w * p1[3] + w2.w * g[3]) * v[3];
;                         *(uint2*)(hid + (size_t)row * FH + hc) = pk4(o);
.LBB0_1064:
	v_mov_b32_e32 v230, 0xbdd2d3e7
	v_mov_b32_e32 v231, 0xbdd2d3e7
	v_mov_b32_e32 v232, 0xc0135761
	v_mov_b32_e32 v233, 0xc0135761
	v_mov_b32_e32 v234, 1.0
	v_mov_b32_e32 v235, 1.0
	s_lshl_b32 s5, s6, 8
	v_mov_b32_e32 v180, v196
	v_mov_b32_e32 v64, v197
	s_or_b32 s5, s5, s49
	s_lshl_b32 s4, s4, 8
	v_lshl_add_u32 v72, v64, 3, s5
	v_ashrrev_i32_e32 v184, 1, v72
	v_ashrrev_i32_e32 v185, 31, v184
	v_lshlrev_b64 v[188:189], 2, v[184:185]
	v_lshl_add_u64 v[64:65], s[58:59], 0, v[188:189]
	v_lshl_add_u64 v[66:67], s[22:23], 0, v[188:189]
	v_lshl_add_u64 v[68:69], s[24:25], 0, v[188:189]
	v_lshl_add_u64 v[70:71], s[60:61], 0, v[188:189]
	global_load_dwordx4 v[140:143], v[64:65], off
	global_load_dwordx4 v[144:147], v[66:67], off
	global_load_dwordx4 v[148:151], v[68:69], off
	global_load_dwordx4 v[156:159], v[70:71], off
	v_add_u32_e32 v64, 0x80, v72
	v_ashrrev_i32_e32 v178, 1, v64
	v_ashrrev_i32_e32 v179, 31, v178
	v_lshlrev_b64 v[182:183], 2, v[178:179]
	v_lshl_add_u64 v[64:65], s[58:59], 0, v[182:183]
	v_lshl_add_u64 v[66:67], s[22:23], 0, v[182:183]
	v_lshl_add_u64 v[76:77], s[24:25], 0, v[182:183]
	v_lshl_add_u64 v[78:79], s[60:61], 0, v[182:183]
	global_load_dwordx4 v[68:71], v[64:65], off
	global_load_dwordx4 v[72:75], v[66:67], off
	s_nop 0
	global_load_dwordx4 v[64:67], v[76:77], off
	s_nop 0
	global_load_dwordx4 v[76:79], v[78:79], off
	s_add_i32 s4, s4, s48
	v_add_u32_e32 v202, s4, v180
	v_cmp_eq_u32_e64 s[4:5], 15, v180
	v_mov_b32_e32 v192, 0
	v_cmp_lt_i32_e32 vcc, 13, v180
	v_cndmask_b32_e64 v168, v136, 0, s[4:5]
	v_mov_b32_e32 v194, 0
	v_mov_b32_e32 v193, 0
	v_mov_b32_dpp v192, v168 row_ror:1 row_mask:0xf bank_mask:0xf
	v_cndmask_b32_e64 v168, v136, 0, vcc
	v_mov_b32_e32 v195, 0
	v_mov_b32_e32 v186, 0
	v_mov_b32_dpp v194, v168 row_ror:2 row_mask:0xf bank_mask:0xf
	v_cndmask_b32_e64 v168, v137, 0, s[4:5]
	v_mov_b32_e32 v190, 0
	v_mov_b32_e32 v187, 0
	v_mov_b32_dpp v193, v168 row_ror:1 row_mask:0xf bank_mask:0xf
	v_cndmask_b32_e64 v168, v137, 0, vcc
	v_mov_b32_e32 v191, 0
	v_cmp_lt_i32_e64 s[6:7], 1, v180
	v_mov_b32_dpp v195, v168 row_ror:2 row_mask:0xf bank_mask:0xf
	v_cndmask_b32_e64 v168, v138, 0, s[4:5]
	s_nop 1
	v_mov_b32_dpp v186, v168 row_ror:1 row_mask:0xf bank_mask:0xf
	v_cndmask_b32_e64 v168, v138, 0, vcc
	s_nop 1
	v_mov_b32_dpp v190, v168 row_ror:2 row_mask:0xf bank_mask:0xf
	v_cndmask_b32_e64 v168, v139, 0, s[4:5]
	s_nop 1
	v_mov_b32_dpp v187, v168 row_ror:1 row_mask:0xf bank_mask:0xf
	v_cndmask_b32_e64 v168, v139, 0, vcc
	s_nop 1
	v_mov_b32_dpp v191, v168 row_ror:2 row_mask:0xf bank_mask:0xf
	s_and_saveexec_b64 s[36:37], s[6:7]
	s_xor_b64 s[36:37], exec, s[36:37]
	s_cbranch_execz .LBB0_1066
	s_waitcnt vmcnt(0)
	v_pk_fma_f32 v[194:195], v[140:141], v[194:195], v[156:157]
	v_pk_fma_f32 v[190:191], v[142:143], v[190:191], v[158:159]
	v_pk_fma_f32 v[192:193], v[144:145], v[192:193], v[194:195]
	v_pk_fma_f32 v[186:187], v[146:147], v[186:187], v[190:191]
	v_pk_fma_f32 v[192:193], v[136:137], v[148:149], v[192:193]
	v_pk_fma_f32 v[186:187], v[138:139], v[150:151], v[186:187]
	v_pk_mul_f32 v[228:229], v[192:193], v[192:193]
	v_pk_fma_f32 v[228:229], v[228:229], v[230:231], v[232:233]
	v_pk_mul_f32 v[228:229], v[228:229], v[192:193]
	v_exp_f32_e32 v228, v228
	v_exp_f32_e32 v229, v229
	s_nop 0
	v_pk_add_f32 v[228:229], v[228:229], v[234:235]
	v_rcp_f32_e32 v194, v228
	v_rcp_f32_e32 v195, v229
	s_nop 0
	v_pk_mul_f32 v[192:193], v[192:193], v[194:195]
	v_pk_mul_f32 v[228:229], v[186:187], v[186:187]
	v_pk_fma_f32 v[228:229], v[228:229], v[230:231], v[232:233]
	v_pk_mul_f32 v[228:229], v[228:229], v[186:187]
	v_exp_f32_e32 v228, v228
	v_exp_f32_e32 v229, v229
	s_nop 0
	v_pk_add_f32 v[228:229], v[228:229], v[234:235]
	v_rcp_f32_e32 v190, v228
	v_rcp_f32_e32 v191, v229
	s_nop 0
	v_pk_mul_f32 v[186:187], v[186:187], v[190:191]
	s_nop 0
	v_pk_mul_f32 v[186:187], v[154:155], v[186:187]
	v_pk_mul_f32 v[192:193], v[152:153], v[192:193]
	v_cvt_pk_bf16_f32 v191, v186, v187
	v_mov_b64_e32 v[186:187], s[72:73]
	v_mad_i64_i32 v[186:187], s[38:39], v202, s76, v[186:187]
	v_cvt_pk_bf16_f32 v190, v192, v193
	v_lshl_add_u64 v[186:187], v[184:185], 1, v[186:187]
	global_store_dwordx2 v[186:187], v[190:191], off

; DI uint2 pk4(f32x4 v) { return make_uint2(pk2(v[0], v[1]), pk2(v[2], v[3])); }
; DI float gelu_t(float x) { float u = 1.5957691216057308f * (x + 0.044715f * x * x * x); return x * __builtin_amdgcn_rcpf(1.f + __expf(-u)); }
;     DI void operator()(const f32x4 (&acc)[2][2][4][2], const pg8::Unit& u, int wr, int wc, int fr, int fq) const {
;     ...
;                     const f32x4 v = acc[ai][bj][m][0], g = acc[ai][bj][m][1];
;                     f32x4 p1, p2;
; #pragma unroll
;                     for (int r = 0; r < 4; ++r) {
;                         p1[r] = __builtin_bit_cast(float, __builtin_amdgcn_update_dpp(0, __builtin_bit_cast(int, (fr == 15) ? gprev[r] : g[r]), 0x121, 0xF, 0xF, false));
;                         p2[r] = __builtin_bit_cast(float, __builtin_amdgcn_update_dpp(0, __builtin_bit_cast(int, (fr >= 14) ? gprev[r] : g[r]), 0x122, 0xF, 0xF, false));
;                     }
;                     const int row = u.pm * 256 + ai * 128 + wr * 64 + m * 16 + fr;
;                     const int wb = row >> 6;
;                     if (m == 0 && fr < 2) {
;                         *(f32x4*)(gfirst + ((size_t)wb * 2 + fr) * FH + hc) = g;
;                         *(f32x4*)(vfirst + ((size_t)wb * 2 + fr) * FH + hc) = v;
;                     } else {
;                         f32x4 o;
;                         o[0] = gelu_t(bb.x + w0.x * p2[0] + w1.x * p1[0] + w2.x * g[0]) * v[0];
;                         o[1] = gelu_t(bb.y + w0.y * p2[1] + w1.y * p1[1] + w2.y * g[1]) * v[1];
;                         o[2] = gelu_t(bb.z + w0.z * p2[2] + w1.z * p1[2] + w2.z * g[2]) * v[2];
;                         o[3] = gelu_t(bb.w + w0.w * p2[3] + w1.w * p1[3] + w2.w * g[3]) * v[3];
;                         *(uint2*)(hid + (size_t)row * FH + hc) = pk4(o);
.LBB0_1068:
	s_or_b64 exec, exec, s[36:37]
	s_nop 0
	v_cndmask_b32_e64 v153, v128, v136, s[4:5]
	v_cndmask_b32_e64 v154, v129, v137, s[4:5]
	v_cndmask_b32_e64 v155, v130, v138, s[4:5]
	v_mov_b32_dpp v152, v153 row_ror:1 row_mask:0xf bank_mask:0xf
	v_cndmask_b32_e32 v153, v128, v136, vcc
	v_cndmask_b32_e64 v190, v131, v139, s[4:5]
	v_add_u32_e32 v168, -14, v180
	v_mov_b32_dpp v136, v153 row_ror:2 row_mask:0xf bank_mask:0xf
	s_nop 1
	v_mov_b32_dpp v153, v154 row_ror:1 row_mask:0xf bank_mask:0xf
	v_cndmask_b32_e32 v154, v129, v137, vcc
	s_nop 1
	v_mov_b32_dpp v137, v154 row_ror:2 row_mask:0xf bank_mask:0xf
	s_waitcnt vmcnt(0)
	v_pk_fma_f32 v[136:137], v[140:141], v[136:137], v[156:157]
	v_mov_b32_dpp v154, v155 row_ror:1 row_mask:0xf bank_mask:0xf
	v_cndmask_b32_e32 v155, v130, v138, vcc
	v_pk_fma_f32 v[136:137], v[144:145], v[152:153], v[136:137]
	s_nop 0
	v_mov_b32_dpp v138, v155 row_ror:2 row_mask:0xf bank_mask:0xf
	v_pk_fma_f32 v[136:137], v[128:129], v[148:149], v[136:137]
	s_nop 0
	v_mov_b32_dpp v155, v190 row_ror:1 row_mask:0xf bank_mask:0xf
	v_cndmask_b32_e32 v190, v131, v139, vcc
	s_nop 1
	v_mov_b32_dpp v139, v190 row_ror:2 row_mask:0xf bank_mask:0xf
	v_pk_fma_f32 v[138:139], v[142:143], v[138:139], v[158:159]
	v_pk_fma_f32 v[138:139], v[146:147], v[154:155], v[138:139]
	v_pk_fma_f32 v[138:139], v[130:131], v[150:151], v[138:139]
	v_pk_mul_f32 v[228:229], v[136:137], v[136:137]
	v_pk_fma_f32 v[228:229], v[228:229], v[230:231], v[232:233]
	v_pk_mul_f32 v[228:229], v[228:229], v[136:137]
	v_exp_f32_e32 v228, v228
	v_exp_f32_e32 v229, v229
	s_nop 0
	v_pk_add_f32 v[228:229], v[228:229], v[234:235]
	v_rcp_f32_e32 v152, v228
	v_rcp_f32_e32 v153, v229
	s_nop 0
	v_pk_mul_f32 v[136:137], v[136:137], v[152:153]
	v_add_u32_e32 v190, 16, v202
	v_pk_mul_f32 v[132:133], v[132:133], v[136:137]
	v_pk_mul_f32 v[228:229], v[138:139], v[138:139]
	v_pk_fma_f32 v[228:229], v[228:229], v[230:231], v[232:233]
	v_pk_mul_f32 v[228:229], v[228:229], v[138:139]
	v_exp_f32_e32 v228, v228
	v_exp_f32_e32 v229, v229
	s_nop 0
	v_pk_add_f32 v[228:229], v[228:229], v[234:235]
	v_rcp_f32_e32 v154, v228
	v_rcp_f32_e32 v155, v229
	s_nop 0
	v_pk_mul_f32 v[136:137], v[138:139], v[154:155]
	v_mov_b64_e32 v[138:139], s[72:73]
	v_pk_mul_f32 v[134:135], v[134:135], v[136:137]
	v_cvt_pk_bf16_f32 v136, v132, v133
	v_cvt_pk_bf16_f32 v137, v134, v135
	v_mad_i64_i32 v[132:133], s[36:37], v190, s76, v[138:139]
	v_lshlrev_b64 v[134:135], 1, v[184:185]
	v_lshl_add_u64 v[152:153], v[132:133], 0, v[134:135]
	global_store_dwordx2 v[152:153], v[136:137], off
	v_cndmask_b32_e64 v137, v120, v128, s[4:5]
	v_cndmask_b32_e64 v152, v121, v129, s[4:5]
	v_cndmask_b32_e64 v153, v122, v130, s[4:5]
	v_mov_b32_dpp v136, v137 row_ror:1 row_mask:0xf bank_mask:0xf
	v_cndmask_b32_e32 v137, v120, v128, vcc
	v_cndmask_b32_e64 v154, v123, v131, s[4:5]
	s_nop 0
	v_mov_b32_dpp v128, v137 row_ror:2 row_mask:0xf bank_mask:0xf
	s_nop 1
	v_mov_b32_dpp v137, v152 row_ror:1 row_mask:0xf bank_mask:0xf
	v_cndmask_b32_e32 v152, v121, v129, vcc
	s_nop 1
	v_mov_b32_dpp v129, v152 row_ror:2 row_mask:0xf bank_mask:0xf
	v_pk_fma_f32 v[128:129], v[140:141], v[128:129], v[156:157]
	s_nop 0
	v_mov_b32_dpp v152, v153 row_ror:1 row_mask:0xf bank_mask:0xf
	v_cndmask_b32_e32 v153, v122, v130, vcc
	v_pk_fma_f32 v[128:129], v[144:145], v[136:137], v[128:129]
	s_nop 0
	v_mov_b32_dpp v130, v153 row_ror:2 row_mask:0xf bank_mask:0xf
	v_pk_fma_f32 v[128:129], v[120:121], v[148:149], v[128:129]
	s_nop 0
	v_mov_b32_dpp v153, v154 row_ror:1 row_mask:0xf bank_mask:0xf
	v_cndmask_b32_e32 v154, v123, v131, vcc
	s_nop 1
	v_mov_b32_dpp v131, v154 row_ror:2 row_mask:0xf bank_mask:0xf
	v_pk_fma_f32 v[130:131], v[142:143], v[130:131], v[158:159]
	v_pk_fma_f32 v[130:131], v[146:147], v[152:153], v[130:131]
	v_pk_fma_f32 v[130:131], v[122:123], v[150:151], v[130:131]
	v_pk_mul_f32 v[228:229], v[128:129], v[128:129]
	v_pk_fma_f32 v[228:229], v[228:229], v[230:231], v[232:233]
	v_pk_mul_f32 v[228:229], v[228:229], v[128:129]
	v_exp_f32_e32 v228, v228
	v_exp_f32_e32 v229, v229
	s_nop 0
	v_pk_add_f32 v[228:229], v[228:229], v[234:235]
	v_rcp_f32_e32 v136, v228
	v_rcp_f32_e32 v137, v229
	s_nop 0
	v_pk_mul_f32 v[128:129], v[128:129], v[136:137]
	v_add_u32_e32 v154, 32, v202
	v_pk_mul_f32 v[124:125], v[124:125], v[128:129]
	v_pk_mul_f32 v[228:229], v[130:131], v[130:131]
	v_pk_fma_f32 v[228:229], v[228:229], v[230:231], v[232:233]
	v_pk_mul_f32 v[228:229], v[228:229], v[130:131]
	v_exp_f32_e32 v228, v228
	v_exp_f32_e32 v229, v229
	s_nop 0
	v_pk_add_f32 v[228:229], v[228:229], v[234:235]
	v_rcp_f32_e32 v152, v228
	v_rcp_f32_e32 v153, v229
	s_nop 0
	v_pk_mul_f32 v[128:129], v[130:131], v[152:153]
	v_cndmask_b32_e64 v130, v115, v123, s[4:5]
	v_pk_mul_f32 v[126:127], v[126:127], v[128:129]
	v_cvt_pk_bf16_f32 v128, v124, v125
	v_mad_i64_i32 v[124:125], s[36:37], v154, s76, v[138:139]
	v_cvt_pk_bf16_f32 v129, v126, v127
	v_lshl_add_u64 v[126:127], v[124:125], 0, v[134:135]
	global_store_dwordx2 v[126:127], v[128:129], off
	v_cndmask_b32_e64 v127, v112, v120, s[4:5]
	v_cndmask_b32_e64 v128, v113, v121, s[4:5]
	v_cndmask_b32_e64 v129, v114, v122, s[4:5]
	v_mov_b32_dpp v126, v127 row_ror:1 row_mask:0xf bank_mask:0xf
; DI uint2 pk4(f32x4 v) { return make_uint2(pk2(v[0], v[1]), pk2(v[2], v[3])); }
; DI float gelu_t(float x) { float u = 1.5957691216057308f * (x + 0.044715f * x * x * x); return x * __builtin_amdgcn_rcpf(1.f + __expf(-u)); }
;     DI void operator()(const f32x4 (&acc)[2][2][4][2], const pg8::Unit& u, int wr, int wc, int fr, int fq) const {
;     ...
;                 f32x4 gprev = (f32x4){0.f, 0.f, 0.f, 0.f};
; #pragma unroll
;                 for (int m = 0; m < 4; ++m) {
;                     const f32x4 v = acc[ai][bj][m][0], g = acc[ai][bj][m][1];
;                     f32x4 p1, p2;
; #pragma unroll
;                     for (int r = 0; r < 4; ++r) {
;                         p1[r] = __builtin_bit_cast(float, __builtin_amdgcn_update_dpp(0, __builtin_bit_cast(int, (fr == 15) ? gprev[r] : g[r]), 0x121, 0xF, 0xF, false));
;                         p2[r] = __builtin_bit_cast(float, __builtin_amdgcn_update_dpp(0, __builtin_bit_cast(int, (fr >= 14) ? gprev[r] : g[r]), 0x122, 0xF, 0xF, false));
;                     }
;                     const int row = u.pm * 256 + ai * 128 + wr * 64 + m * 16 + fr;
;                     const int wb = row >> 6;
;                     if (m == 0 && fr < 2) {
;                         *(f32x4*)(gfirst + ((size_t)wb * 2 + fr) * FH + hc) = g;
;                         *(f32x4*)(vfirst + ((size_t)wb * 2 + fr) * FH + hc) = v;
;                     } else {
;                         f32x4 o;
;                         o[0] = gelu_t(bb.x + w0.x * p2[0] + w1.x * p1[0] + w2.x * g[0]) * v[0];
;                         o[1] = gelu_t(bb.y + w0.y * p2[1] + w1.y * p1[1] + w2.y * g[1]) * v[1];
;                         o[2] = gelu_t(bb.z + w0.z * p2[2] + w1.z * p1[2] + w2.z * g[2]) * v[2];
;                         o[3] = gelu_t(bb.w + w0.w * p2[3] + w1.w * p1[3] + w2.w * g[3]) * v[3];
;                         *(uint2*)(hid + (size_t)row * FH + hc) = pk4(o);
;                     }
;                     if (m == 3 && fr >= 14) *(f32x4*)(glast + ((size_t)wb * 2 + (fr - 14)) * FH + hc) = g;
;                     gprev = g;
	v_cndmask_b32_e32 v127, v112, v120, vcc
	v_add_u32_e32 v136, 48, v202
	s_nop 0
	v_mov_b32_dpp v120, v127 row_ror:2 row_mask:0xf bank_mask:0xf
	s_nop 1
	v_mov_b32_dpp v127, v128 row_ror:1 row_mask:0xf bank_mask:0xf
	v_cndmask_b32_e32 v128, v113, v121, vcc
	s_nop 1
	v_mov_b32_dpp v121, v128 row_ror:2 row_mask:0xf bank_mask:0xf
	v_pk_fma_f32 v[120:121], v[140:141], v[120:121], v[156:157]
	v_pk_fma_f32 v[120:121], v[144:145], v[126:127], v[120:121]
	s_nop 0
	v_pk_fma_f32 v[126:127], v[112:113], v[148:149], v[120:121]
	v_mov_b32_dpp v128, v129 row_ror:1 row_mask:0xf bank_mask:0xf
	v_cndmask_b32_e32 v129, v114, v122, vcc
	s_nop 1
	v_mov_b32_dpp v122, v129 row_ror:2 row_mask:0xf bank_mask:0xf
	v_mov_b32_dpp v129, v130 row_ror:1 row_mask:0xf bank_mask:0xf
	v_cndmask_b32_e32 v130, v115, v123, vcc
	s_nop 1
	v_mov_b32_dpp v123, v130 row_ror:2 row_mask:0xf bank_mask:0xf
	v_pk_fma_f32 v[120:121], v[142:143], v[122:123], v[158:159]
	v_pk_mul_f32 v[228:229], v[126:127], v[126:127]
	v_pk_fma_f32 v[228:229], v[228:229], v[230:231], v[232:233]
	v_pk_mul_f32 v[228:229], v[228:229], v[126:127]
	v_exp_f32_e32 v228, v228
	v_exp_f32_e32 v229, v229
	s_nop 0
	v_pk_add_f32 v[228:229], v[228:229], v[234:235]
	v_rcp_f32_e32 v130, v228
	v_rcp_f32_e32 v131, v229
	s_nop 0
	v_pk_mul_f32 v[126:127], v[126:127], v[130:131]
	v_pk_fma_f32 v[120:121], v[146:147], v[128:129], v[120:121]
	v_pk_mul_f32 v[116:117], v[116:117], v[126:127]
	v_pk_fma_f32 v[122:123], v[114:115], v[150:151], v[120:121]
	s_nop 0
	v_ashrrev_i32_e32 v120, 6, v136
	v_ashrrev_i32_e32 v121, 31, v120
	v_pk_mul_f32 v[228:229], v[122:123], v[122:123]
	v_pk_fma_f32 v[228:229], v[228:229], v[230:231], v[232:233]
	v_pk_mul_f32 v[228:229], v[228:229], v[122:123]
	v_exp_f32_e32 v228, v228
	v_exp_f32_e32 v229, v229
	s_nop 0
	v_pk_add_f32 v[228:229], v[228:229], v[234:235]
	v_rcp_f32_e32 v128, v228
	v_rcp_f32_e32 v129, v229
	s_nop 0
	v_pk_mul_f32 v[122:123], v[122:123], v[128:129]
	s_nop 0
	v_pk_mul_f32 v[118:119], v[118:119], v[122:123]
	v_cvt_pk_bf16_f32 v122, v116, v117
	v_mad_i64_i32 v[116:117], s[36:37], v136, s76, v[138:139]
	v_cvt_pk_bf16_f32 v123, v118, v119
	v_lshl_add_u64 v[118:119], v[116:117], 0, v[134:135]
	global_store_dwordx2 v[118:119], v[122:123], off
	s_and_saveexec_b64 s[36:37], vcc
	s_cbranch_execz .LBB0_1070
	v_lshl_add_u64 v[118:119], v[120:121], 1, v[168:169]
	v_mov_b64_e32 v[122:123], s[68:69]
	v_mad_u64_u32 v[122:123], s[38:39], v118, s77, v[122:123]
	v_mad_i32_i24 v123, v119, s77, v123
	v_lshl_add_u64 v[118:119], v[184:185], 2, v[122:123]
	global_store_dwordx4 v[118:119], v[112:115], off
.LBB0_1070:
	s_or_b64 exec, exec, s[36:37]
	s_nop 0
	v_cndmask_b32_e64 v112, v104, 0, s[4:5]
	s_nop 1
	v_mov_b32_dpp v118, v112 row_ror:1 row_mask:0xf bank_mask:0xf
	v_cndmask_b32_e64 v112, v104, 0, vcc
	v_cndmask_b32_e64 v113, v106, 0, s[4:5]
	s_nop 0
	v_mov_b32_dpp v122, v112 row_ror:2 row_mask:0xf bank_mask:0xf
	v_cndmask_b32_e64 v112, v105, 0, s[4:5]
	v_cndmask_b32_e64 v115, v107, 0, s[4:5]
	s_nop 0
	v_mov_b32_dpp v119, v112 row_ror:1 row_mask:0xf bank_mask:0xf
	v_cndmask_b32_e64 v112, v105, 0, vcc
	v_cndmask_b32_e64 v127, v107, 0, vcc
	v_add_u32_e32 v126, 0x80, v202
	v_mov_b32_dpp v123, v112 row_ror:2 row_mask:0xf bank_mask:0xf
	s_nop 1
	v_mov_b32_dpp v112, v113 row_ror:1 row_mask:0xf bank_mask:0xf
	v_cndmask_b32_e64 v113, v106, 0, vcc
	s_nop 1
	v_mov_b32_dpp v114, v113 row_ror:2 row_mask:0xf bank_mask:0xf
	s_nop 1
	v_mov_b32_dpp v113, v115 row_ror:1 row_mask:0xf bank_mask:0xf
	s_nop 1
	v_mov_b32_dpp v115, v127 row_ror:2 row_mask:0xf bank_mask:0xf
	s_and_saveexec_b64 s[36:37], s[6:7]
	s_xor_b64 s[36:37], exec, s[36:37]
	s_cbranch_execz .LBB0_1072
	v_pk_fma_f32 v[114:115], v[142:143], v[114:115], v[158:159]
	v_pk_fma_f32 v[122:123], v[140:141], v[122:123], v[156:157]
	v_pk_fma_f32 v[112:113], v[146:147], v[112:113], v[114:115]
	v_pk_fma_f32 v[118:119], v[144:145], v[118:119], v[122:123]
	v_pk_fma_f32 v[112:113], v[106:107], v[150:151], v[112:113]
	v_pk_fma_f32 v[118:119], v[104:105], v[148:149], v[118:119]
	v_pk_mul_f32 v[228:229], v[112:113], v[112:113]
	v_pk_fma_f32 v[228:229], v[228:229], v[230:231], v[232:233]
	v_pk_mul_f32 v[228:229], v[228:229], v[112:113]
	v_exp_f32_e32 v228, v228
	v_exp_f32_e32 v229, v229
	s_nop 0
	v_pk_add_f32 v[228:229], v[228:229], v[234:235]
	v_rcp_f32_e32 v114, v228
	v_rcp_f32_e32 v115, v229
	s_nop 0
	v_pk_mul_f32 v[112:113], v[112:113], v[114:115]
	v_pk_mul_f32 v[228:229], v[118:119], v[118:119]
	v_pk_fma_f32 v[228:229], v[228:229], v[230:231], v[232:233]
	v_pk_mul_f32 v[228:229], v[228:229], v[118:119]
	v_exp_f32_e32 v228, v228
	v_exp_f32_e32 v229, v229
	s_nop 0
	v_pk_add_f32 v[228:229], v[228:229], v[234:235]
	v_rcp_f32_e32 v122, v228
	v_rcp_f32_e32 v123, v229
	s_nop 0
	v_pk_mul_f32 v[118:119], v[118:119], v[122:123]
	v_pk_mul_f32 v[112:113], v[110:111], v[112:113]
	v_pk_mul_f32 v[118:119], v[108:109], v[118:119]
	v_cvt_pk_bf16_f32 v115, v112, v113
	v_mov_b64_e32 v[112:113], s[72:73]
	v_mad_i64_i32 v[112:113], s[38:39], v126, s76, v[112:113]
	v_cvt_pk_bf16_f32 v114, v118, v119
	v_lshl_add_u64 v[112:113], v[184:185], 1, v[112:113]
	global_store_dwordx2 v[112:113], v[114:115], off

; DI uint2 pk4(f32x4 v) { return make_uint2(pk2(v[0], v[1]), pk2(v[2], v[3])); }
; DI float gelu_t(float x) { float u = 1.5957691216057308f * (x + 0.044715f * x * x * x); return x * __builtin_amdgcn_rcpf(1.f + __expf(-u)); }
;     DI void operator()(const f32x4 (&acc)[2][2][4][2], const pg8::Unit& u, int wr, int wc, int fr, int fq) const {
;     ...
;                     const f32x4 v = acc[ai][bj][m][0], g = acc[ai][bj][m][1];
;                     f32x4 p1, p2;
; #pragma unroll
;                     for (int r = 0; r < 4; ++r) {
;                         p1[r] = __builtin_bit_cast(float, __builtin_amdgcn_update_dpp(0, __builtin_bit_cast(int, (fr == 15) ? gprev[r] : g[r]), 0x121, 0xF, 0xF, false));
;                         p2[r] = __builtin_bit_cast(float, __builtin_amdgcn_update_dpp(0, __builtin_bit_cast(int, (fr >= 14) ? gprev[r] : g[r]), 0x122, 0xF, 0xF, false));
;                     }
;                     const int row = u.pm * 256 + ai * 128 + wr * 64 + m * 16 + fr;
;                     const int wb = row >> 6;
;                     if (m == 0 && fr < 2) {
;                         *(f32x4*)(gfirst + ((size_t)wb * 2 + fr) * FH + hc) = g;
;                         *(f32x4*)(vfirst + ((size_t)wb * 2 + fr) * FH + hc) = v;
;                     } else {
;                         f32x4 o;
;                         o[0] = gelu_t(bb.x + w0.x * p2[0] + w1.x * p1[0] + w2.x * g[0]) * v[0];
;                         o[1] = gelu_t(bb.y + w0.y * p2[1] + w1.y * p1[1] + w2.y * g[1]) * v[1];
;                         o[2] = gelu_t(bb.z + w0.z * p2[2] + w1.z * p1[2] + w2.z * g[2]) * v[2];
;                         o[3] = gelu_t(bb.w + w0.w * p2[3] + w1.w * p1[3] + w2.w * g[3]) * v[3];
;                         *(uint2*)(hid + (size_t)row * FH + hc) = pk4(o);
.LBB0_1074:
	s_or_b64 exec, exec, s[36:37]
	s_nop 0
	v_cndmask_b32_e64 v109, v96, v104, s[4:5]
	v_cndmask_b32_e64 v110, v97, v105, s[4:5]
	v_cndmask_b32_e64 v111, v98, v106, s[4:5]
	v_mov_b32_dpp v108, v109 row_ror:1 row_mask:0xf bank_mask:0xf
	v_cndmask_b32_e32 v109, v96, v104, vcc
	v_cndmask_b32_e64 v114, v99, v107, s[4:5]
	s_nop 0
	v_mov_b32_dpp v104, v109 row_ror:2 row_mask:0xf bank_mask:0xf
	s_nop 1
	v_mov_b32_dpp v109, v110 row_ror:1 row_mask:0xf bank_mask:0xf
	v_cndmask_b32_e32 v110, v97, v105, vcc
	s_nop 1
	v_mov_b32_dpp v105, v110 row_ror:2 row_mask:0xf bank_mask:0xf
	v_pk_fma_f32 v[104:105], v[140:141], v[104:105], v[156:157]
	s_nop 0
	v_mov_b32_dpp v110, v111 row_ror:1 row_mask:0xf bank_mask:0xf
	v_cndmask_b32_e32 v111, v98, v106, vcc
	v_pk_fma_f32 v[104:105], v[144:145], v[108:109], v[104:105]
	s_nop 0
	v_mov_b32_dpp v106, v111 row_ror:2 row_mask:0xf bank_mask:0xf
	v_pk_fma_f32 v[104:105], v[96:97], v[148:149], v[104:105]
	s_nop 0
	v_mov_b32_dpp v111, v114 row_ror:1 row_mask:0xf bank_mask:0xf
	v_cndmask_b32_e32 v114, v99, v107, vcc
	s_nop 1
	v_mov_b32_dpp v107, v114 row_ror:2 row_mask:0xf bank_mask:0xf
	v_pk_fma_f32 v[106:107], v[142:143], v[106:107], v[158:159]
	v_pk_fma_f32 v[106:107], v[146:147], v[110:111], v[106:107]
	v_pk_fma_f32 v[106:107], v[98:99], v[150:151], v[106:107]
	v_pk_mul_f32 v[228:229], v[104:105], v[104:105]
	v_pk_fma_f32 v[228:229], v[228:229], v[230:231], v[232:233]
	v_pk_mul_f32 v[228:229], v[228:229], v[104:105]
	v_exp_f32_e32 v228, v228
	v_exp_f32_e32 v229, v229
	s_nop 0
	v_pk_add_f32 v[228:229], v[228:229], v[234:235]
	v_rcp_f32_e32 v108, v228
	v_rcp_f32_e32 v109, v229
	s_nop 0
	v_pk_mul_f32 v[104:105], v[104:105], v[108:109]
	v_add_u32_e32 v114, 0x90, v202
	v_pk_mul_f32 v[100:101], v[100:101], v[104:105]
	v_pk_mul_f32 v[228:229], v[106:107], v[106:107]
	v_pk_fma_f32 v[228:229], v[228:229], v[230:231], v[232:233]
	v_pk_mul_f32 v[228:229], v[228:229], v[106:107]
	v_exp_f32_e32 v228, v228
	v_exp_f32_e32 v229, v229
	s_nop 0
	v_pk_add_f32 v[228:229], v[228:229], v[234:235]
	v_rcp_f32_e32 v110, v228
	v_rcp_f32_e32 v111, v229
	s_nop 0
	v_pk_mul_f32 v[104:105], v[106:107], v[110:111]
	v_cndmask_b32_e64 v108, v91, v99, s[4:5]
	v_pk_mul_f32 v[102:103], v[102:103], v[104:105]
	v_cvt_pk_bf16_f32 v104, v100, v101
	v_cvt_pk_bf16_f32 v105, v102, v103
	v_mov_b64_e32 v[102:103], s[72:73]
	v_mad_i64_i32 v[100:101], s[36:37], v114, s76, v[102:103]
	v_lshl_add_u64 v[106:107], v[100:101], 0, v[134:135]
	global_store_dwordx2 v[106:107], v[104:105], off
	v_cndmask_b32_e64 v105, v88, v96, s[4:5]
	v_cndmask_b32_e64 v106, v89, v97, s[4:5]
	v_cndmask_b32_e64 v107, v90, v98, s[4:5]
	v_mov_b32_dpp v104, v105 row_ror:1 row_mask:0xf bank_mask:0xf
	v_cndmask_b32_e32 v105, v88, v96, vcc
	s_nop 1
	v_mov_b32_dpp v96, v105 row_ror:2 row_mask:0xf bank_mask:0xf
	s_nop 1
	v_mov_b32_dpp v105, v106 row_ror:1 row_mask:0xf bank_mask:0xf
	v_cndmask_b32_e32 v106, v89, v97, vcc
	s_nop 1
	v_mov_b32_dpp v97, v106 row_ror:2 row_mask:0xf bank_mask:0xf
	v_pk_fma_f32 v[96:97], v[140:141], v[96:97], v[156:157]
	s_nop 0
	v_mov_b32_dpp v106, v107 row_ror:1 row_mask:0xf bank_mask:0xf
	v_cndmask_b32_e32 v107, v90, v98, vcc
	v_pk_fma_f32 v[96:97], v[144:145], v[104:105], v[96:97]
	s_nop 0
	v_mov_b32_dpp v98, v107 row_ror:2 row_mask:0xf bank_mask:0xf
	v_pk_fma_f32 v[96:97], v[88:89], v[148:149], v[96:97]
	s_nop 0
	v_mov_b32_dpp v107, v108 row_ror:1 row_mask:0xf bank_mask:0xf
	v_cndmask_b32_e32 v108, v91, v99, vcc
	s_nop 1
	v_mov_b32_dpp v99, v108 row_ror:2 row_mask:0xf bank_mask:0xf
	v_pk_fma_f32 v[98:99], v[142:143], v[98:99], v[158:159]
	v_pk_fma_f32 v[98:99], v[146:147], v[106:107], v[98:99]
	v_pk_fma_f32 v[98:99], v[90:91], v[150:151], v[98:99]
	v_pk_mul_f32 v[228:229], v[96:97], v[96:97]
	v_pk_fma_f32 v[228:229], v[228:229], v[230:231], v[232:233]
	v_pk_mul_f32 v[228:229], v[228:229], v[96:97]
	v_exp_f32_e32 v228, v228
	v_exp_f32_e32 v229, v229
	s_nop 0
	v_pk_add_f32 v[228:229], v[228:229], v[234:235]
	v_rcp_f32_e32 v104, v228
	v_rcp_f32_e32 v105, v229
	s_nop 0
	v_pk_mul_f32 v[96:97], v[96:97], v[104:105]
	v_add_u32_e32 v108, 0xa0, v202
	v_pk_mul_f32 v[92:93], v[92:93], v[96:97]
	v_pk_mul_f32 v[228:229], v[98:99], v[98:99]
	v_pk_fma_f32 v[228:229], v[228:229], v[230:231], v[232:233]
	v_pk_mul_f32 v[228:229], v[228:229], v[98:99]
	v_exp_f32_e32 v228, v228
	v_exp_f32_e32 v229, v229
	s_nop 0
	v_pk_add_f32 v[228:229], v[228:229], v[234:235]
	v_rcp_f32_e32 v106, v228
	v_rcp_f32_e32 v107, v229
	s_nop 0
	v_pk_mul_f32 v[96:97], v[98:99], v[106:107]
	v_cndmask_b32_e64 v98, v83, v91, s[4:5]
	v_pk_mul_f32 v[94:95], v[94:95], v[96:97]
	v_cvt_pk_bf16_f32 v96, v92, v93
	v_mad_i64_i32 v[92:93], s[36:37], v108, s76, v[102:103]
	v_cvt_pk_bf16_f32 v97, v94, v95
	v_lshl_add_u64 v[94:95], v[92:93], 0, v[134:135]
	global_store_dwordx2 v[94:95], v[96:97], off
	v_cndmask_b32_e64 v95, v80, v88, s[4:5]
	v_cndmask_b32_e64 v96, v81, v89, s[4:5]
	v_cndmask_b32_e64 v97, v82, v90, s[4:5]
; DI uint2 pk4(f32x4 v) { return make_uint2(pk2(v[0], v[1]), pk2(v[2], v[3])); }
; DI float gelu_t(float x) { float u = 1.5957691216057308f * (x + 0.044715f * x * x * x); return x * __builtin_amdgcn_rcpf(1.f + __expf(-u)); }
;     DI void operator()(const f32x4 (&acc)[2][2][4][2], const pg8::Unit& u, int wr, int wc, int fr, int fq) const {
;     ...
;                 f32x4 gprev = (f32x4){0.f, 0.f, 0.f, 0.f};
; #pragma unroll
;                 for (int m = 0; m < 4; ++m) {
;                     const f32x4 v = acc[ai][bj][m][0], g = acc[ai][bj][m][1];
;                     f32x4 p1, p2;
; #pragma unroll
;                     for (int r = 0; r < 4; ++r) {
;                         p1[r] = __builtin_bit_cast(float, __builtin_amdgcn_update_dpp(0, __builtin_bit_cast(int, (fr == 15) ? gprev[r] : g[r]), 0x121, 0xF, 0xF, false));
;                         p2[r] = __builtin_bit_cast(float, __builtin_amdgcn_update_dpp(0, __builtin_bit_cast(int, (fr >= 14) ? gprev[r] : g[r]), 0x122, 0xF, 0xF, false));
;                     }
;                     const int row = u.pm * 256 + ai * 128 + wr * 64 + m * 16 + fr;
;                     const int wb = row >> 6;
;                     if (m == 0 && fr < 2) {
;                         *(f32x4*)(gfirst + ((size_t)wb * 2 + fr) * FH + hc) = g;
;                         *(f32x4*)(vfirst + ((size_t)wb * 2 + fr) * FH + hc) = v;
;                     } else {
;                         f32x4 o;
;                         o[0] = gelu_t(bb.x + w0.x * p2[0] + w1.x * p1[0] + w2.x * g[0]) * v[0];
;                         o[1] = gelu_t(bb.y + w0.y * p2[1] + w1.y * p1[1] + w2.y * g[1]) * v[1];
;                         o[2] = gelu_t(bb.z + w0.z * p2[2] + w1.z * p1[2] + w2.z * g[2]) * v[2];
;                         o[3] = gelu_t(bb.w + w0.w * p2[3] + w1.w * p1[3] + w2.w * g[3]) * v[3];
;                         *(uint2*)(hid + (size_t)row * FH + hc) = pk4(o);
;                     }
;                     if (m == 3 && fr >= 14) *(f32x4*)(glast + ((size_t)wb * 2 + (fr - 14)) * FH + hc) = g;
;                     gprev = g;
	v_mov_b32_dpp v94, v95 row_ror:1 row_mask:0xf bank_mask:0xf
	v_cndmask_b32_e32 v95, v80, v88, vcc
	v_add_u32_e32 v104, 0xb0, v202
	s_nop 0
	v_mov_b32_dpp v88, v95 row_ror:2 row_mask:0xf bank_mask:0xf
	s_nop 1
	v_mov_b32_dpp v95, v96 row_ror:1 row_mask:0xf bank_mask:0xf
	v_cndmask_b32_e32 v96, v81, v89, vcc
	s_nop 1
	v_mov_b32_dpp v89, v96 row_ror:2 row_mask:0xf bank_mask:0xf
	v_pk_fma_f32 v[88:89], v[140:141], v[88:89], v[156:157]
	v_pk_fma_f32 v[88:89], v[144:145], v[94:95], v[88:89]
	s_nop 0
	v_pk_fma_f32 v[94:95], v[80:81], v[148:149], v[88:89]
	v_mov_b32_dpp v96, v97 row_ror:1 row_mask:0xf bank_mask:0xf
	v_cndmask_b32_e32 v97, v82, v90, vcc
	s_nop 1
	v_mov_b32_dpp v90, v97 row_ror:2 row_mask:0xf bank_mask:0xf
	v_mov_b32_dpp v97, v98 row_ror:1 row_mask:0xf bank_mask:0xf
	v_cndmask_b32_e32 v98, v83, v91, vcc
	s_nop 1
	v_mov_b32_dpp v91, v98 row_ror:2 row_mask:0xf bank_mask:0xf
	v_pk_fma_f32 v[88:89], v[142:143], v[90:91], v[158:159]
	v_pk_mul_f32 v[228:229], v[94:95], v[94:95]
	v_pk_fma_f32 v[228:229], v[228:229], v[230:231], v[232:233]
	v_pk_mul_f32 v[228:229], v[228:229], v[94:95]
	v_exp_f32_e32 v228, v228
	v_exp_f32_e32 v229, v229
	s_nop 0
	v_pk_add_f32 v[228:229], v[228:229], v[234:235]
	v_rcp_f32_e32 v98, v228
	v_rcp_f32_e32 v99, v229
	s_nop 0
	v_pk_mul_f32 v[94:95], v[94:95], v[98:99]
	v_pk_fma_f32 v[88:89], v[146:147], v[96:97], v[88:89]
	v_pk_mul_f32 v[84:85], v[84:85], v[94:95]
	v_pk_fma_f32 v[90:91], v[82:83], v[150:151], v[88:89]
	s_nop 0
	v_ashrrev_i32_e32 v88, 6, v104
	v_ashrrev_i32_e32 v89, 31, v88
	v_pk_mul_f32 v[228:229], v[90:91], v[90:91]
	v_pk_fma_f32 v[228:229], v[228:229], v[230:231], v[232:233]
	v_pk_mul_f32 v[228:229], v[228:229], v[90:91]
	v_exp_f32_e32 v228, v228
	v_exp_f32_e32 v229, v229
	s_nop 0
	v_pk_add_f32 v[228:229], v[228:229], v[234:235]
	v_rcp_f32_e32 v96, v228
	v_rcp_f32_e32 v97, v229
	s_nop 0
	v_pk_mul_f32 v[90:91], v[90:91], v[96:97]
	s_nop 0
	v_pk_mul_f32 v[86:87], v[86:87], v[90:91]
	v_cvt_pk_bf16_f32 v90, v84, v85
	v_mad_i64_i32 v[84:85], s[36:37], v104, s76, v[102:103]
	v_cvt_pk_bf16_f32 v91, v86, v87
	v_lshl_add_u64 v[86:87], v[84:85], 0, v[134:135]
	global_store_dwordx2 v[86:87], v[90:91], off
	s_and_saveexec_b64 s[36:37], vcc
	s_cbranch_execz .LBB0_1076
	v_lshl_add_u64 v[86:87], v[88:89], 1, v[168:169]
	v_mov_b64_e32 v[90:91], s[68:69]
	v_mad_u64_u32 v[90:91], s[38:39], v86, s77, v[90:91]
	v_mad_i32_i24 v91, v87, s77, v91
	v_lshl_add_u64 v[86:87], v[184:185], 2, v[90:91]
	global_store_dwordx4 v[86:87], v[80:83], off
.LBB0_1076:
	s_or_b64 exec, exec, s[36:37]
	s_nop 0
	v_cndmask_b32_e64 v80, v56, 0, s[4:5]
	s_nop 1
	v_mov_b32_dpp v86, v80 row_ror:1 row_mask:0xf bank_mask:0xf
	v_cndmask_b32_e64 v80, v56, 0, vcc
	v_cndmask_b32_e64 v81, v58, 0, s[4:5]
	s_nop 0
	v_mov_b32_dpp v90, v80 row_ror:2 row_mask:0xf bank_mask:0xf
	v_cndmask_b32_e64 v80, v57, 0, s[4:5]
	v_cndmask_b32_e64 v83, v59, 0, s[4:5]
	s_nop 0
	v_mov_b32_dpp v87, v80 row_ror:1 row_mask:0xf bank_mask:0xf
	v_cndmask_b32_e64 v80, v57, 0, vcc
	v_cndmask_b32_e64 v94, v59, 0, vcc
	s_nop 0
	v_mov_b32_dpp v91, v80 row_ror:2 row_mask:0xf bank_mask:0xf
	s_nop 1
	v_mov_b32_dpp v80, v81 row_ror:1 row_mask:0xf bank_mask:0xf
	v_cndmask_b32_e64 v81, v58, 0, vcc
	s_nop 1
	v_mov_b32_dpp v82, v81 row_ror:2 row_mask:0xf bank_mask:0xf
	s_nop 1
	v_mov_b32_dpp v81, v83 row_ror:1 row_mask:0xf bank_mask:0xf
	s_nop 1
	v_mov_b32_dpp v83, v94 row_ror:2 row_mask:0xf bank_mask:0xf
	s_and_saveexec_b64 s[36:37], s[6:7]
	s_xor_b64 s[36:37], exec, s[36:37]
	s_cbranch_execz .LBB0_1078
	v_pk_fma_f32 v[82:83], v[70:71], v[82:83], v[78:79]
	v_pk_fma_f32 v[90:91], v[68:69], v[90:91], v[76:77]
	v_pk_fma_f32 v[80:81], v[74:75], v[80:81], v[82:83]
	v_pk_fma_f32 v[86:87], v[72:73], v[86:87], v[90:91]
	v_pk_fma_f32 v[80:81], v[58:59], v[66:67], v[80:81]
	v_pk_fma_f32 v[86:87], v[56:57], v[64:65], v[86:87]
	v_pk_mul_f32 v[228:229], v[80:81], v[80:81]
	v_pk_fma_f32 v[228:229], v[228:229], v[230:231], v[232:233]
	v_pk_mul_f32 v[228:229], v[228:229], v[80:81]
	v_exp_f32_e32 v228, v228
	v_exp_f32_e32 v229, v229
	s_nop 0
	v_pk_add_f32 v[228:229], v[228:229], v[234:235]
	v_rcp_f32_e32 v82, v228
	v_rcp_f32_e32 v83, v229
	s_nop 0
	v_pk_mul_f32 v[80:81], v[80:81], v[82:83]
	v_pk_mul_f32 v[228:229], v[86:87], v[86:87]
	v_pk_fma_f32 v[228:229], v[228:229], v[230:231], v[232:233]
	v_pk_mul_f32 v[228:229], v[228:229], v[86:87]
	v_exp_f32_e32 v228, v228
	v_exp_f32_e32 v229, v229
	s_nop 0
	v_pk_add_f32 v[228:229], v[228:229], v[234:235]
	v_rcp_f32_e32 v90, v228
	v_rcp_f32_e32 v91, v229
	s_nop 0
	v_pk_mul_f32 v[86:87], v[86:87], v[90:91]
	v_pk_mul_f32 v[80:81], v[62:63], v[80:81]
	v_pk_mul_f32 v[86:87], v[60:61], v[86:87]
	v_cvt_pk_bf16_f32 v83, v80, v81
	v_mov_b64_e32 v[80:81], s[72:73]
	v_mad_i64_i32 v[80:81], s[38:39], v202, s76, v[80:81]
	v_cvt_pk_bf16_f32 v82, v86, v87
	v_lshl_add_u64 v[80:81], v[178:179], 1, v[80:81]
	global_store_dwordx2 v[80:81], v[82:83], off

; DI uint2 pk4(f32x4 v) { return make_uint2(pk2(v[0], v[1]), pk2(v[2], v[3])); }
; DI float gelu_t(float x) { float u = 1.5957691216057308f * (x + 0.044715f * x * x * x); return x * __builtin_amdgcn_rcpf(1.f + __expf(-u)); }
;     DI void operator()(const f32x4 (&acc)[2][2][4][2], const pg8::Unit& u, int wr, int wc, int fr, int fq) const {
;     ...
;                     const f32x4 v = acc[ai][bj][m][0], g = acc[ai][bj][m][1];
;                     f32x4 p1, p2;
; #pragma unroll
;                     for (int r = 0; r < 4; ++r) {
;                         p1[r] = __builtin_bit_cast(float, __builtin_amdgcn_update_dpp(0, __builtin_bit_cast(int, (fr == 15) ? gprev[r] : g[r]), 0x121, 0xF, 0xF, false));
;                         p2[r] = __builtin_bit_cast(float, __builtin_amdgcn_update_dpp(0, __builtin_bit_cast(int, (fr >= 14) ? gprev[r] : g[r]), 0x122, 0xF, 0xF, false));
;                     }
;                     const int row = u.pm * 256 + ai * 128 + wr * 64 + m * 16 + fr;
;                     const int wb = row >> 6;
;                     if (m == 0 && fr < 2) {
;                         *(f32x4*)(gfirst + ((size_t)wb * 2 + fr) * FH + hc) = g;
;                         *(f32x4*)(vfirst + ((size_t)wb * 2 + fr) * FH + hc) = v;
;                     } else {
;                         f32x4 o;
;                         o[0] = gelu_t(bb.x + w0.x * p2[0] + w1.x * p1[0] + w2.x * g[0]) * v[0];
;                         o[1] = gelu_t(bb.y + w0.y * p2[1] + w1.y * p1[1] + w2.y * g[1]) * v[1];
;                         o[2] = gelu_t(bb.z + w0.z * p2[2] + w1.z * p1[2] + w2.z * g[2]) * v[2];
;                         o[3] = gelu_t(bb.w + w0.w * p2[3] + w1.w * p1[3] + w2.w * g[3]) * v[3];
;                         *(uint2*)(hid + (size_t)row * FH + hc) = pk4(o);
;                     }
;                     if (m == 3 && fr >= 14) *(f32x4*)(glast + ((size_t)wb * 2 + (fr - 14)) * FH + hc) = g;
;                     gprev = g;
.LBB0_1080:
	s_or_b64 exec, exec, s[36:37]
	s_nop 0
	v_cndmask_b32_e64 v61, v48, v56, s[4:5]
	v_cndmask_b32_e64 v62, v49, v57, s[4:5]
	v_cndmask_b32_e64 v63, v50, v58, s[4:5]
	v_mov_b32_dpp v60, v61 row_ror:1 row_mask:0xf bank_mask:0xf
	v_cndmask_b32_e32 v61, v48, v56, vcc
	v_cndmask_b32_e64 v80, v51, v59, s[4:5]
	s_nop 0
	v_mov_b32_dpp v56, v61 row_ror:2 row_mask:0xf bank_mask:0xf
	s_nop 1
	v_mov_b32_dpp v61, v62 row_ror:1 row_mask:0xf bank_mask:0xf
	v_cndmask_b32_e32 v62, v49, v57, vcc
	s_nop 1
	v_mov_b32_dpp v57, v62 row_ror:2 row_mask:0xf bank_mask:0xf
	v_pk_fma_f32 v[56:57], v[68:69], v[56:57], v[76:77]
	s_nop 0
	v_mov_b32_dpp v62, v63 row_ror:1 row_mask:0xf bank_mask:0xf
	v_cndmask_b32_e32 v63, v50, v58, vcc
	v_pk_fma_f32 v[56:57], v[72:73], v[60:61], v[56:57]
	s_nop 0
	v_mov_b32_dpp v58, v63 row_ror:2 row_mask:0xf bank_mask:0xf
	v_pk_fma_f32 v[56:57], v[48:49], v[64:65], v[56:57]
	s_nop 0
	v_mov_b32_dpp v63, v80 row_ror:1 row_mask:0xf bank_mask:0xf
	v_cndmask_b32_e32 v80, v51, v59, vcc
	s_nop 1
	v_mov_b32_dpp v59, v80 row_ror:2 row_mask:0xf bank_mask:0xf
	v_pk_fma_f32 v[58:59], v[70:71], v[58:59], v[78:79]
	v_pk_fma_f32 v[58:59], v[74:75], v[62:63], v[58:59]
	v_pk_fma_f32 v[58:59], v[50:51], v[66:67], v[58:59]
	v_pk_mul_f32 v[228:229], v[56:57], v[56:57]
	v_pk_fma_f32 v[228:229], v[228:229], v[230:231], v[232:233]
	v_pk_mul_f32 v[228:229], v[228:229], v[56:57]
	v_exp_f32_e32 v228, v228
	v_exp_f32_e32 v229, v229
	s_nop 0
	v_pk_add_f32 v[228:229], v[228:229], v[234:235]
	v_rcp_f32_e32 v60, v228
	v_rcp_f32_e32 v61, v229
	s_nop 0
	v_pk_mul_f32 v[56:57], v[56:57], v[60:61]
	v_cndmask_b32_e64 v60, v41, v49, s[4:5]
	v_pk_mul_f32 v[52:53], v[52:53], v[56:57]
	v_pk_mul_f32 v[228:229], v[58:59], v[58:59]
	v_pk_fma_f32 v[228:229], v[228:229], v[230:231], v[232:233]
	v_pk_mul_f32 v[228:229], v[228:229], v[58:59]
	v_exp_f32_e32 v228, v228
	v_exp_f32_e32 v229, v229
	s_nop 0
	v_pk_add_f32 v[228:229], v[228:229], v[234:235]
	v_rcp_f32_e32 v62, v228
	v_rcp_f32_e32 v63, v229
	s_nop 0
	v_pk_mul_f32 v[56:57], v[58:59], v[62:63]
	v_cndmask_b32_e64 v59, v40, v48, s[4:5]
	v_cndmask_b32_e64 v61, v42, v50, s[4:5]
	v_cndmask_b32_e64 v62, v43, v51, s[4:5]
	v_mov_b32_dpp v58, v59 row_ror:1 row_mask:0xf bank_mask:0xf
	v_cndmask_b32_e32 v59, v40, v48, vcc
	v_pk_mul_f32 v[54:55], v[54:55], v[56:57]
	v_cvt_pk_bf16_f32 v56, v52, v53
	v_mov_b32_dpp v48, v59 row_ror:2 row_mask:0xf bank_mask:0xf
	v_lshlrev_b64 v[52:53], 1, v[178:179]
	v_cvt_pk_bf16_f32 v57, v54, v55
	v_mov_b32_dpp v59, v60 row_ror:1 row_mask:0xf bank_mask:0xf
	v_cndmask_b32_e32 v60, v41, v49, vcc
	v_lshl_add_u64 v[54:55], v[132:133], 0, v[52:53]
	global_store_dwordx2 v[54:55], v[56:57], off
	v_mov_b32_dpp v49, v60 row_ror:2 row_mask:0xf bank_mask:0xf
	v_pk_fma_f32 v[48:49], v[68:69], v[48:49], v[76:77]
	v_cndmask_b32_e64 v54, v35, v43, s[4:5]
	v_mov_b32_dpp v60, v61 row_ror:1 row_mask:0xf bank_mask:0xf
	v_cndmask_b32_e32 v61, v42, v50, vcc
	v_pk_fma_f32 v[48:49], v[72:73], v[58:59], v[48:49]
	s_nop 0
	v_mov_b32_dpp v50, v61 row_ror:2 row_mask:0xf bank_mask:0xf
	v_pk_fma_f32 v[48:49], v[40:41], v[64:65], v[48:49]
	s_nop 0
	v_mov_b32_dpp v61, v62 row_ror:1 row_mask:0xf bank_mask:0xf
	v_cndmask_b32_e32 v62, v43, v51, vcc
	s_nop 1
	v_mov_b32_dpp v51, v62 row_ror:2 row_mask:0xf bank_mask:0xf
	v_pk_fma_f32 v[50:51], v[70:71], v[50:51], v[78:79]
	v_pk_fma_f32 v[50:51], v[74:75], v[60:61], v[50:51]
	v_pk_fma_f32 v[50:51], v[42:43], v[66:67], v[50:51]
	v_pk_mul_f32 v[228:229], v[48:49], v[48:49]
	v_pk_fma_f32 v[228:229], v[228:229], v[230:231], v[232:233]
	v_pk_mul_f32 v[228:229], v[228:229], v[48:49]
	v_exp_f32_e32 v228, v228
	v_exp_f32_e32 v229, v229
	s_nop 0
	v_pk_add_f32 v[228:229], v[228:229], v[234:235]
	v_rcp_f32_e32 v58, v228
	v_rcp_f32_e32 v59, v229
	s_nop 0
	v_pk_mul_f32 v[48:49], v[48:49], v[58:59]
	s_nop 0
	v_pk_mul_f32 v[44:45], v[44:45], v[48:49]
	v_pk_mul_f32 v[228:229], v[50:51], v[50:51]
	v_pk_fma_f32 v[228:229], v[228:229], v[230:231], v[232:233]
	v_pk_mul_f32 v[228:229], v[228:229], v[50:51]
	v_exp_f32_e32 v228, v228
	v_exp_f32_e32 v229, v229
	s_nop 0
	v_pk_add_f32 v[228:229], v[228:229], v[234:235]
	v_rcp_f32_e32 v60, v228
	v_rcp_f32_e32 v61, v229
	s_nop 0
	v_pk_mul_f32 v[48:49], v[50:51], v[60:61]
	v_cndmask_b32_e64 v50, v33, v41, s[4:5]
	v_pk_mul_f32 v[46:47], v[46:47], v[48:49]
	v_cndmask_b32_e64 v49, v32, v40, s[4:5]
	v_cndmask_b32_e64 v51, v34, v42, s[4:5]
	v_cvt_pk_bf16_f32 v44, v44, v45
	v_mov_b32_dpp v48, v49 row_ror:1 row_mask:0xf bank_mask:0xf
	v_cndmask_b32_e32 v49, v32, v40, vcc
	v_cvt_pk_bf16_f32 v45, v46, v47
	v_lshl_add_u64 v[46:47], v[124:125], 0, v[52:53]
	v_mov_b32_dpp v40, v49 row_ror:2 row_mask:0xf bank_mask:0xf
	global_store_dwordx2 v[46:47], v[44:45], off
	s_nop 0
	v_mov_b32_dpp v49, v50 row_ror:1 row_mask:0xf bank_mask:0xf
	v_cndmask_b32_e32 v50, v33, v41, vcc
	s_nop 1
	v_mov_b32_dpp v41, v50 row_ror:2 row_mask:0xf bank_mask:0xf
	v_pk_fma_f32 v[40:41], v[68:69], v[40:41], v[76:77]
	s_nop 0
	v_mov_b32_dpp v50, v51 row_ror:1 row_mask:0xf bank_mask:0xf
	v_cndmask_b32_e32 v51, v34, v42, vcc
	v_pk_fma_f32 v[40:41], v[72:73], v[48:49], v[40:41]
	s_nop 0
	v_mov_b32_dpp v42, v51 row_ror:2 row_mask:0xf bank_mask:0xf
	v_pk_fma_f32 v[40:41], v[32:33], v[64:65], v[40:41]
	s_nop 0
	v_mov_b32_dpp v51, v54 row_ror:1 row_mask:0xf bank_mask:0xf
	v_cndmask_b32_e32 v54, v35, v43, vcc
	s_nop 1
	v_mov_b32_dpp v43, v54 row_ror:2 row_mask:0xf bank_mask:0xf
	v_pk_fma_f32 v[42:43], v[70:71], v[42:43], v[78:79]
	v_pk_fma_f32 v[42:43], v[74:75], v[50:51], v[42:43]
	v_pk_fma_f32 v[42:43], v[34:35], v[66:67], v[42:43]
	v_pk_mul_f32 v[228:229], v[40:41], v[40:41]
	v_pk_fma_f32 v[228:229], v[228:229], v[230:231], v[232:233]
	v_pk_mul_f32 v[228:229], v[228:229], v[40:41]
	v_exp_f32_e32 v228, v228
	v_exp_f32_e32 v229, v229
	s_nop 0
	v_pk_add_f32 v[228:229], v[228:229], v[234:235]
	v_rcp_f32_e32 v48, v228
	v_rcp_f32_e32 v49, v229
	s_nop 0
	v_pk_mul_f32 v[40:41], v[40:41], v[48:49]
	s_nop 0
	v_pk_mul_f32 v[36:37], v[36:37], v[40:41]
	v_pk_mul_f32 v[228:229], v[42:43], v[42:43]
	v_pk_fma_f32 v[228:229], v[228:229], v[230:231], v[232:233]
	v_pk_mul_f32 v[228:229], v[228:229], v[42:43]
	v_exp_f32_e32 v228, v228
	v_exp_f32_e32 v229, v229
	s_nop 0
	v_pk_add_f32 v[228:229], v[228:229], v[234:235]
	v_rcp_f32_e32 v50, v228
	v_rcp_f32_e32 v51, v229
	s_nop 0
	v_pk_mul_f32 v[40:41], v[42:43], v[50:51]
	v_cvt_pk_bf16_f32 v36, v36, v37
	v_pk_mul_f32 v[38:39], v[38:39], v[40:41]
	s_nop 0
	v_cvt_pk_bf16_f32 v37, v38, v39
	v_lshl_add_u64 v[38:39], v[116:117], 0, v[52:53]
	global_store_dwordx2 v[38:39], v[36:37], off
	s_and_saveexec_b64 s[36:37], vcc
	s_cbranch_execz .LBB0_1082
	v_lshl_add_u64 v[36:37], v[120:121], 1, v[168:169]
	v_mov_b64_e32 v[38:39], s[68:69]
	v_mad_u64_u32 v[38:39], s[38:39], v36, s77, v[38:39]
	v_mad_i32_i24 v39, v37, s77, v39
	v_lshl_add_u64 v[36:37], v[178:179], 2, v[38:39]
	global_store_dwordx4 v[36:37], v[32:35], off
; DI uint2 pk4(f32x4 v) { return make_uint2(pk2(v[0], v[1]), pk2(v[2], v[3])); }
; DI float gelu_t(float x) { float u = 1.5957691216057308f * (x + 0.044715f * x * x * x); return x * __builtin_amdgcn_rcpf(1.f + __expf(-u)); }
;     DI void operator()(const f32x4 (&acc)[2][2][4][2], const pg8::Unit& u, int wr, int wc, int fr, int fq) const {
;     ...
;                 f32x4 gprev = (f32x4){0.f, 0.f, 0.f, 0.f};
; #pragma unroll
;                 for (int m = 0; m < 4; ++m) {
;                     const f32x4 v = acc[ai][bj][m][0], g = acc[ai][bj][m][1];
;                     f32x4 p1, p2;
; #pragma unroll
;                     for (int r = 0; r < 4; ++r) {
;                         p1[r] = __builtin_bit_cast(float, __builtin_amdgcn_update_dpp(0, __builtin_bit_cast(int, (fr == 15) ? gprev[r] : g[r]), 0x121, 0xF, 0xF, false));
;                         p2[r] = __builtin_bit_cast(float, __builtin_amdgcn_update_dpp(0, __builtin_bit_cast(int, (fr >= 14) ? gprev[r] : g[r]), 0x122, 0xF, 0xF, false));
;                     }
;                     const int row = u.pm * 256 + ai * 128 + wr * 64 + m * 16 + fr;
;                     const int wb = row >> 6;
;                     if (m == 0 && fr < 2) {
;                         *(f32x4*)(gfirst + ((size_t)wb * 2 + fr) * FH + hc) = g;
;                         *(f32x4*)(vfirst + ((size_t)wb * 2 + fr) * FH + hc) = v;
;                     } else {
;                         f32x4 o;
;                         o[0] = gelu_t(bb.x + w0.x * p2[0] + w1.x * p1[0] + w2.x * g[0]) * v[0];
;                         o[1] = gelu_t(bb.y + w0.y * p2[1] + w1.y * p1[1] + w2.y * g[1]) * v[1];
;                         o[2] = gelu_t(bb.z + w0.z * p2[2] + w1.z * p1[2] + w2.z * g[2]) * v[2];
;                         o[3] = gelu_t(bb.w + w0.w * p2[3] + w1.w * p1[3] + w2.w * g[3]) * v[3];
;                         *(uint2*)(hid + (size_t)row * FH + hc) = pk4(o);
.LBB0_1082:
	s_or_b64 exec, exec, s[36:37]
	s_nop 0
	v_cndmask_b32_e64 v32, v24, 0, s[4:5]
	s_nop 1
	v_mov_b32_dpp v36, v32 row_ror:1 row_mask:0xf bank_mask:0xf
	v_cndmask_b32_e64 v32, v24, 0, vcc
	v_cndmask_b32_e64 v33, v26, 0, s[4:5]
	s_nop 0
	v_mov_b32_dpp v38, v32 row_ror:2 row_mask:0xf bank_mask:0xf
	v_cndmask_b32_e64 v32, v25, 0, s[4:5]
	v_cndmask_b32_e64 v35, v27, 0, s[4:5]
	s_nop 0
	v_mov_b32_dpp v37, v32 row_ror:1 row_mask:0xf bank_mask:0xf
	v_cndmask_b32_e64 v32, v25, 0, vcc
	v_cndmask_b32_e64 v40, v27, 0, vcc
	s_nop 0
	v_mov_b32_dpp v39, v32 row_ror:2 row_mask:0xf bank_mask:0xf
	s_nop 1
	v_mov_b32_dpp v32, v33 row_ror:1 row_mask:0xf bank_mask:0xf
	v_cndmask_b32_e64 v33, v26, 0, vcc
	s_nop 1
	v_mov_b32_dpp v34, v33 row_ror:2 row_mask:0xf bank_mask:0xf
	s_nop 1
	v_mov_b32_dpp v33, v35 row_ror:1 row_mask:0xf bank_mask:0xf
	s_nop 1
	v_mov_b32_dpp v35, v40 row_ror:2 row_mask:0xf bank_mask:0xf
	s_and_saveexec_b64 s[36:37], s[6:7]
	s_xor_b64 s[6:7], exec, s[36:37]
	s_cbranch_execz .LBB0_1084
	v_pk_fma_f32 v[34:35], v[70:71], v[34:35], v[78:79]
	v_pk_fma_f32 v[38:39], v[68:69], v[38:39], v[76:77]
	v_pk_fma_f32 v[32:33], v[74:75], v[32:33], v[34:35]
	v_pk_fma_f32 v[36:37], v[72:73], v[36:37], v[38:39]
	v_pk_fma_f32 v[32:33], v[26:27], v[66:67], v[32:33]
	v_pk_fma_f32 v[36:37], v[24:25], v[64:65], v[36:37]
	v_pk_mul_f32 v[228:229], v[32:33], v[32:33]
	v_pk_fma_f32 v[228:229], v[228:229], v[230:231], v[232:233]
	v_pk_mul_f32 v[228:229], v[228:229], v[32:33]
	v_exp_f32_e32 v228, v228
	v_exp_f32_e32 v229, v229
	s_nop 0
	v_pk_add_f32 v[228:229], v[228:229], v[234:235]
	v_rcp_f32_e32 v34, v228
	v_rcp_f32_e32 v35, v229
	s_nop 0
	v_pk_mul_f32 v[32:33], v[32:33], v[34:35]
	v_pk_mul_f32 v[228:229], v[36:37], v[36:37]
	v_pk_fma_f32 v[228:229], v[228:229], v[230:231], v[232:233]
	v_pk_mul_f32 v[228:229], v[228:229], v[36:37]
	v_exp_f32_e32 v228, v228
	v_exp_f32_e32 v229, v229
	s_nop 0
	v_pk_add_f32 v[228:229], v[228:229], v[234:235]
	v_rcp_f32_e32 v38, v228
	v_rcp_f32_e32 v39, v229
	s_nop 0
	v_pk_mul_f32 v[36:37], v[36:37], v[38:39]
	v_pk_mul_f32 v[32:33], v[30:31], v[32:33]
	v_pk_mul_f32 v[36:37], v[28:29], v[36:37]
	v_cvt_pk_bf16_f32 v35, v32, v33
	v_mov_b64_e32 v[32:33], s[72:73]
	v_mad_i64_i32 v[32:33], s[36:37], v126, s76, v[32:33]
	v_cvt_pk_bf16_f32 v34, v36, v37
	v_lshl_add_u64 v[32:33], v[178:179], 1, v[32:33]
	global_store_dwordx2 v[32:33], v[34:35], off

; DI uint2 pk4(f32x4 v) { return make_uint2(pk2(v[0], v[1]), pk2(v[2], v[3])); }
; DI float gelu_t(float x) { float u = 1.5957691216057308f * (x + 0.044715f * x * x * x); return x * __builtin_amdgcn_rcpf(1.f + __expf(-u)); }
;     DI void operator()(const f32x4 (&acc)[2][2][4][2], const pg8::Unit& u, int wr, int wc, int fr, int fq) const {
;     ...
;                     const f32x4 v = acc[ai][bj][m][0], g = acc[ai][bj][m][1];
;                     f32x4 p1, p2;
; #pragma unroll
;                     for (int r = 0; r < 4; ++r) {
;                         p1[r] = __builtin_bit_cast(float, __builtin_amdgcn_update_dpp(0, __builtin_bit_cast(int, (fr == 15) ? gprev[r] : g[r]), 0x121, 0xF, 0xF, false));
;                         p2[r] = __builtin_bit_cast(float, __builtin_amdgcn_update_dpp(0, __builtin_bit_cast(int, (fr >= 14) ? gprev[r] : g[r]), 0x122, 0xF, 0xF, false));
;                     }
;                     const int row = u.pm * 256 + ai * 128 + wr * 64 + m * 16 + fr;
;                     const int wb = row >> 6;
;                     if (m == 0 && fr < 2) {
;                         *(f32x4*)(gfirst + ((size_t)wb * 2 + fr) * FH + hc) = g;
;                         *(f32x4*)(vfirst + ((size_t)wb * 2 + fr) * FH + hc) = v;
;                     } else {
;                         f32x4 o;
;                         o[0] = gelu_t(bb.x + w0.x * p2[0] + w1.x * p1[0] + w2.x * g[0]) * v[0];
;                         o[1] = gelu_t(bb.y + w0.y * p2[1] + w1.y * p1[1] + w2.y * g[1]) * v[1];
;                         o[2] = gelu_t(bb.z + w0.z * p2[2] + w1.z * p1[2] + w2.z * g[2]) * v[2];
;                         o[3] = gelu_t(bb.w + w0.w * p2[3] + w1.w * p1[3] + w2.w * g[3]) * v[3];
;                         *(uint2*)(hid + (size_t)row * FH + hc) = pk4(o);
;                     }
;                     if (m == 3 && fr >= 14) *(f32x4*)(glast + ((size_t)wb * 2 + (fr - 14)) * FH + hc) = g;
;                     gprev = g;
.LBB0_1086:
	s_or_b64 exec, exec, s[6:7]
	s_nop 0
	v_cndmask_b32_e64 v29, v16, v24, s[4:5]
	v_cndmask_b32_e64 v30, v17, v25, s[4:5]
	v_cndmask_b32_e64 v31, v18, v26, s[4:5]
	v_mov_b32_dpp v28, v29 row_ror:1 row_mask:0xf bank_mask:0xf
	v_cndmask_b32_e32 v29, v16, v24, vcc
	v_cndmask_b32_e64 v32, v19, v27, s[4:5]
	s_nop 0
	v_mov_b32_dpp v24, v29 row_ror:2 row_mask:0xf bank_mask:0xf
	s_nop 1
	v_mov_b32_dpp v29, v30 row_ror:1 row_mask:0xf bank_mask:0xf
	v_cndmask_b32_e32 v30, v17, v25, vcc
	s_nop 1
	v_mov_b32_dpp v25, v30 row_ror:2 row_mask:0xf bank_mask:0xf
	v_pk_fma_f32 v[24:25], v[68:69], v[24:25], v[76:77]
	s_nop 0
	v_mov_b32_dpp v30, v31 row_ror:1 row_mask:0xf bank_mask:0xf
	v_cndmask_b32_e32 v31, v18, v26, vcc
	v_pk_fma_f32 v[24:25], v[72:73], v[28:29], v[24:25]
	s_nop 0
	v_mov_b32_dpp v26, v31 row_ror:2 row_mask:0xf bank_mask:0xf
	v_pk_fma_f32 v[24:25], v[16:17], v[64:65], v[24:25]
	s_nop 0
	v_mov_b32_dpp v31, v32 row_ror:1 row_mask:0xf bank_mask:0xf
	v_cndmask_b32_e32 v32, v19, v27, vcc
	s_nop 1
	v_mov_b32_dpp v27, v32 row_ror:2 row_mask:0xf bank_mask:0xf
	v_pk_fma_f32 v[26:27], v[70:71], v[26:27], v[78:79]
	v_pk_fma_f32 v[26:27], v[74:75], v[30:31], v[26:27]
	v_pk_fma_f32 v[26:27], v[18:19], v[66:67], v[26:27]
	v_pk_mul_f32 v[228:229], v[24:25], v[24:25]
	v_pk_fma_f32 v[228:229], v[228:229], v[230:231], v[232:233]
	v_pk_mul_f32 v[228:229], v[228:229], v[24:25]
	v_exp_f32_e32 v228, v228
	v_exp_f32_e32 v229, v229
	s_nop 0
	v_pk_add_f32 v[228:229], v[228:229], v[234:235]
	v_rcp_f32_e32 v28, v228
	v_rcp_f32_e32 v29, v229
	s_nop 0
	v_pk_mul_f32 v[24:25], v[24:25], v[28:29]
	v_cndmask_b32_e64 v28, v11, v19, s[4:5]
	v_pk_mul_f32 v[20:21], v[20:21], v[24:25]
	v_pk_mul_f32 v[228:229], v[26:27], v[26:27]
	v_pk_fma_f32 v[228:229], v[228:229], v[230:231], v[232:233]
	v_pk_mul_f32 v[228:229], v[228:229], v[26:27]
	v_exp_f32_e32 v228, v228
	v_exp_f32_e32 v229, v229
	s_nop 0
	v_pk_add_f32 v[228:229], v[228:229], v[234:235]
	v_rcp_f32_e32 v30, v228
	v_rcp_f32_e32 v31, v229
	s_nop 0
	v_pk_mul_f32 v[24:25], v[26:27], v[30:31]
	v_cndmask_b32_e64 v26, v9, v17, s[4:5]
	v_pk_mul_f32 v[22:23], v[22:23], v[24:25]
	v_cndmask_b32_e64 v25, v8, v16, s[4:5]
	v_cndmask_b32_e64 v27, v10, v18, s[4:5]
	v_cvt_pk_bf16_f32 v20, v20, v21
	v_mov_b32_dpp v24, v25 row_ror:1 row_mask:0xf bank_mask:0xf
	v_cndmask_b32_e32 v25, v8, v16, vcc
	v_cvt_pk_bf16_f32 v21, v22, v23
	v_lshl_add_u64 v[22:23], v[100:101], 0, v[52:53]
	v_mov_b32_dpp v16, v25 row_ror:2 row_mask:0xf bank_mask:0xf
	global_store_dwordx2 v[22:23], v[20:21], off
	v_cndmask_b32_e64 v20, v3, v11, s[4:5]
	v_mov_b32_dpp v25, v26 row_ror:1 row_mask:0xf bank_mask:0xf
	v_cndmask_b32_e32 v26, v9, v17, vcc
	s_nop 1
	v_mov_b32_dpp v17, v26 row_ror:2 row_mask:0xf bank_mask:0xf
	v_pk_fma_f32 v[16:17], v[68:69], v[16:17], v[76:77]
	s_nop 0
	v_mov_b32_dpp v26, v27 row_ror:1 row_mask:0xf bank_mask:0xf
	v_cndmask_b32_e32 v27, v10, v18, vcc
	v_pk_fma_f32 v[16:17], v[72:73], v[24:25], v[16:17]
	s_nop 0
	v_mov_b32_dpp v18, v27 row_ror:2 row_mask:0xf bank_mask:0xf
	v_pk_fma_f32 v[16:17], v[8:9], v[64:65], v[16:17]
	s_nop 0
	v_mov_b32_dpp v27, v28 row_ror:1 row_mask:0xf bank_mask:0xf
	v_cndmask_b32_e32 v28, v11, v19, vcc
	s_nop 1
	v_mov_b32_dpp v19, v28 row_ror:2 row_mask:0xf bank_mask:0xf
	v_pk_fma_f32 v[18:19], v[70:71], v[18:19], v[78:79]
	v_pk_fma_f32 v[18:19], v[74:75], v[26:27], v[18:19]
	v_pk_fma_f32 v[18:19], v[10:11], v[66:67], v[18:19]
	v_pk_mul_f32 v[228:229], v[16:17], v[16:17]
	v_pk_fma_f32 v[228:229], v[228:229], v[230:231], v[232:233]
	v_pk_mul_f32 v[228:229], v[228:229], v[16:17]
	v_exp_f32_e32 v228, v228
	v_exp_f32_e32 v229, v229
	s_nop 0
	v_pk_add_f32 v[228:229], v[228:229], v[234:235]
	v_rcp_f32_e32 v24, v228
	v_rcp_f32_e32 v25, v229
	s_nop 0
	v_pk_mul_f32 v[16:17], v[16:17], v[24:25]
	s_nop 0
	v_pk_mul_f32 v[12:13], v[12:13], v[16:17]
	v_pk_mul_f32 v[228:229], v[18:19], v[18:19]
	v_pk_fma_f32 v[228:229], v[228:229], v[230:231], v[232:233]
	v_pk_mul_f32 v[228:229], v[228:229], v[18:19]
	v_exp_f32_e32 v228, v228
	v_exp_f32_e32 v229, v229
	s_nop 0
	v_pk_add_f32 v[228:229], v[228:229], v[234:235]
	v_rcp_f32_e32 v26, v228
	v_rcp_f32_e32 v27, v229
	s_nop 0
	v_pk_mul_f32 v[16:17], v[18:19], v[26:27]
	v_cndmask_b32_e64 v18, v1, v9, s[4:5]
	v_pk_mul_f32 v[14:15], v[14:15], v[16:17]
	v_cndmask_b32_e64 v17, v0, v8, s[4:5]
	v_cndmask_b32_e64 v19, v2, v10, s[4:5]
	v_cvt_pk_bf16_f32 v12, v12, v13
	v_mov_b32_dpp v16, v17 row_ror:1 row_mask:0xf bank_mask:0xf
	v_cndmask_b32_e32 v17, v0, v8, vcc
	v_cvt_pk_bf16_f32 v13, v14, v15
	v_lshl_add_u64 v[14:15], v[92:93], 0, v[52:53]
	v_mov_b32_dpp v8, v17 row_ror:2 row_mask:0xf bank_mask:0xf
	global_store_dwordx2 v[14:15], v[12:13], off
	s_nop 0
	v_mov_b32_dpp v17, v18 row_ror:1 row_mask:0xf bank_mask:0xf
	v_cndmask_b32_e32 v18, v1, v9, vcc
	s_nop 1
	v_mov_b32_dpp v9, v18 row_ror:2 row_mask:0xf bank_mask:0xf
	v_pk_fma_f32 v[8:9], v[68:69], v[8:9], v[76:77]
	s_nop 0
	v_mov_b32_dpp v18, v19 row_ror:1 row_mask:0xf bank_mask:0xf
	v_cndmask_b32_e32 v19, v2, v10, vcc
	v_pk_fma_f32 v[8:9], v[72:73], v[16:17], v[8:9]
	s_nop 0
	v_mov_b32_dpp v10, v19 row_ror:2 row_mask:0xf bank_mask:0xf
	v_pk_fma_f32 v[8:9], v[0:1], v[64:65], v[8:9]
	s_nop 0
	v_mov_b32_dpp v19, v20 row_ror:1 row_mask:0xf bank_mask:0xf
	v_cndmask_b32_e32 v20, v3, v11, vcc
	s_nop 1
	v_mov_b32_dpp v11, v20 row_ror:2 row_mask:0xf bank_mask:0xf
	v_pk_fma_f32 v[10:11], v[70:71], v[10:11], v[78:79]
	v_pk_fma_f32 v[10:11], v[74:75], v[18:19], v[10:11]
	v_pk_fma_f32 v[10:11], v[2:3], v[66:67], v[10:11]
	v_pk_mul_f32 v[228:229], v[8:9], v[8:9]
	v_pk_fma_f32 v[228:229], v[228:229], v[230:231], v[232:233]
	v_pk_mul_f32 v[228:229], v[228:229], v[8:9]
	v_exp_f32_e32 v228, v228
	v_exp_f32_e32 v229, v229
	s_nop 0
	v_pk_add_f32 v[228:229], v[228:229], v[234:235]
	v_rcp_f32_e32 v16, v228
	v_rcp_f32_e32 v17, v229
	s_nop 0
	v_pk_mul_f32 v[8:9], v[8:9], v[16:17]
	s_nop 0
	v_pk_mul_f32 v[4:5], v[4:5], v[8:9]
	v_pk_mul_f32 v[228:229], v[10:11], v[10:11]
	v_pk_fma_f32 v[228:229], v[228:229], v[230:231], v[232:233]
	v_pk_mul_f32 v[228:229], v[228:229], v[10:11]
	v_exp_f32_e32 v228, v228
	v_exp_f32_e32 v229, v229
	s_nop 0
	v_pk_add_f32 v[228:229], v[228:229], v[234:235]
	v_rcp_f32_e32 v18, v228
	v_rcp_f32_e32 v19, v229
	s_nop 0
	v_pk_mul_f32 v[8:9], v[10:11], v[18:19]
	v_cvt_pk_bf16_f32 v4, v4, v5
	v_pk_mul_f32 v[6:7], v[6:7], v[8:9]
	s_nop 0
	v_cvt_pk_bf16_f32 v5, v6, v7
	v_lshl_add_u64 v[6:7], v[84:85], 0, v[52:53]
	global_store_dwordx2 v[6:7], v[4:5], off
	s_and_saveexec_b64 s[4:5], vcc
	s_cbranch_execz .LBB0_1088
	v_lshl_add_u64 v[4:5], v[88:89], 1, v[168:169]
	v_mov_b64_e32 v[6:7], s[68:69]
	v_mad_u64_u32 v[6:7], s[6:7], v4, s77, v[6:7]
	v_mad_i32_i24 v7, v5, s77, v7
	v_lshl_add_u64 v[4:5], v[178:179], 2, v[6:7]
	global_store_dwordx4 v[4:5], v[0:3], off
